# qkv unit: head weight staging loops unrolled (all loads in flight instead of one round trip per 16 B chunk)
# speedup vs baseline: 1.0273x; 1.0025x over previous
; #define LAS __attribute__((address_space(3)))
; __device__ __forceinline__ void qkv_head_unit(const Params& p, LAS unsigned char* lds, int h, int blk_begin, int blk_end) {
;     ...
;     float frq[4];
; #pragma unroll
;     for (int i = 0; i < 4; ++i) frq[i] = exp2f(-(float)(4 * fq + i) * (13.287712379549449f / 16.0f));
;     __syncthreads();
;     { const bf16_t* W = (const bf16_t*)(ws + WS_WUQ) + (size_t)(96 * h) * 384;
;       for (int idx = tid; idx < 96 * 48; idx += 512) { const int r = idx / 48, c = idx % 48; *(LAS u32x4*)(wl + r * WQS + c * 8) = *(const u32x4*)(W + r * 384 + c * 8); } }
;     __syncthreads();
.LBB0_500:
	v_mov_b32_e32 v135, v163
	s_movk_i32 s8, 0x1200
	v_bfe_u32 v128, v135, 4, 2
	v_lshlrev_b32_e32 v115, 2, v128
	v_cvt_f32_ubyte0_e32 v5, v115
	v_or_b32_e32 v129, 1, v115
	v_mul_f32_e32 v0, 0xbf549a78, v5
	v_cvt_f32_ubyte0_e32 v4, v129
	v_or_b32_e32 v130, 2, v115
	v_cmp_gt_f32_e64 s[2:3], s84, v0
	v_mul_f32_e32 v0, 0xbf549a78, v4
	v_cvt_f32_ubyte0_e32 v3, v130
	v_or_b32_e32 v131, 3, v115
	v_cmp_gt_f32_e64 s[4:5], s84, v0
	v_mul_f32_e32 v0, 0xbf549a78, v3
	v_cvt_f32_ubyte0_e32 v2, v131
	v_cmp_gt_f32_e32 vcc, s84, v0
	v_mul_f32_e32 v0, 0xbf549a78, v2
	s_and_b32 s16, s72, 7
	v_cmp_gt_f32_e64 s[0:1], s84, v0
	v_cmp_gt_i32_e64 s[8:9], s8, v135
	v_lshl_add_u32 v138, v135, 4, 0
	v_lshlrev_b32_e32 v133, 3, v135
	s_barrier
	s_and_saveexec_b64 s[10:11], s[8:9]
	s_cbranch_execz .LBB0_503
	s_mul_i32 s8, s16, 0x12000
	v_readlane_b32 s6, v244, 36
	s_add_u32 s12, s6, s8
	v_readlane_b32 s6, v244, 37
	s_addc_u32 s13, s6, 0
	v_mov_b32_e32 v50, v163
	v_add_u32_e32 v51, 0x200, v163
	v_add_u32_e32 v52, 0x400, v163
	v_add_u32_e32 v53, 0x600, v163
	v_add_u32_e32 v54, 0x800, v163
	v_add_u32_e32 v55, 0xa00, v163
	v_add_u32_e32 v56, 0xc00, v163
	v_add_u32_e32 v57, 0xe00, v163
	v_add_u32_e32 v58, 0x1000, v163
	v_lshlrev_b32_e32 v59, 4, v50
	v_lshlrev_b32_e32 v60, 4, v51
	v_lshlrev_b32_e32 v61, 4, v52
	v_lshlrev_b32_e32 v62, 4, v53
	v_lshlrev_b32_e32 v63, 4, v54
	v_lshlrev_b32_e32 v64, 4, v55
	v_lshlrev_b32_e32 v65, 4, v56
	v_lshlrev_b32_e32 v66, 4, v57
	v_lshlrev_b32_e32 v67, 4, v58
	global_load_dwordx4 v[14:17], v59, s[12:13]
	global_load_dwordx4 v[18:21], v60, s[12:13]
	global_load_dwordx4 v[22:25], v61, s[12:13]
	global_load_dwordx4 v[26:29], v62, s[12:13]
	global_load_dwordx4 v[30:33], v63, s[12:13]
	global_load_dwordx4 v[34:37], v64, s[12:13]
	global_load_dwordx4 v[38:41], v65, s[12:13]
	global_load_dwordx4 v[42:45], v66, s[12:13]
	global_load_dwordx4 v[46:49], v67, s[12:13]
	v_mul_u32_u24_e32 v69, 0xaaab, v50
	v_mul_u32_u24_e32 v70, 0xaaab, v51
	v_mul_u32_u24_e32 v71, 0xaaab, v52
	v_mul_u32_u24_e32 v72, 0xaaab, v53
	v_mul_u32_u24_e32 v73, 0xaaab, v54
	v_mul_u32_u24_e32 v74, 0xaaab, v55
	v_mul_u32_u24_e32 v75, 0xaaab, v56
	v_mul_u32_u24_e32 v76, 0xaaab, v57
	v_mul_u32_u24_e32 v77, 0xaaab, v58
	v_lshrrev_b32_e32 v69, 21, v69
	v_lshrrev_b32_e32 v70, 21, v70
	v_lshrrev_b32_e32 v71, 21, v71
	v_lshrrev_b32_e32 v72, 21, v72
	v_lshrrev_b32_e32 v73, 21, v73
	v_lshrrev_b32_e32 v74, 21, v74
	v_lshrrev_b32_e32 v75, 21, v75
	v_lshrrev_b32_e32 v76, 21, v76
	v_lshrrev_b32_e32 v77, 21, v77
	v_add_lshl_u32 v69, v50, v69, 4
	v_add_lshl_u32 v70, v51, v70, 4
	v_add_lshl_u32 v71, v52, v71, 4
	v_add_lshl_u32 v72, v53, v72, 4
	v_add_lshl_u32 v73, v54, v73, 4
	v_add_lshl_u32 v74, v55, v74, 4
	v_add_lshl_u32 v75, v56, v75, 4
	v_add_lshl_u32 v76, v57, v76, 4
	v_add_lshl_u32 v77, v58, v77, 4
	s_waitcnt vmcnt(8)
	ds_write_b128 v69, v[14:17]
	s_waitcnt vmcnt(7)
	ds_write_b128 v70, v[18:21]
	s_waitcnt vmcnt(6)
	ds_write_b128 v71, v[22:25]
	s_waitcnt vmcnt(5)
	ds_write_b128 v72, v[26:29]
	s_waitcnt vmcnt(4)
	ds_write_b128 v73, v[30:33]
	s_waitcnt vmcnt(3)
	ds_write_b128 v74, v[34:37]
	s_waitcnt vmcnt(2)
	ds_write_b128 v75, v[38:41]
	s_waitcnt vmcnt(1)
	ds_write_b128 v76, v[42:45]
	s_waitcnt vmcnt(0)
	ds_write_b128 v77, v[46:49]

; #define LAS __attribute__((address_space(3)))
; __device__ __forceinline__ void qkv_head_unit(const Params& p, LAS unsigned char* lds, int h, int blk_begin, int blk_end) {
;     ...
;     __syncthreads();
;     { const bf16_t* W = (const bf16_t*)(ws + WS_WUKV) + (size_t)(128 * h) * 256;
;       for (int idx = tid; idx < 128 * 32; idx += 512) { const int r = idx / 32, c = idx % 32; *(LAS u32x4*)(wl + r * WKS + c * 8) = *(const u32x4*)(W + r * 256 + c * 8); } }
;     __syncthreads();
.LBB0_518:
	s_or_b64 exec, exec, s[4:5]
	v_cmp_gt_i32_e64 s[0:1], s85, v135
	s_waitcnt lgkmcnt(0)
	s_barrier
	s_and_saveexec_b64 s[2:3], s[0:1]
	s_cbranch_execz .LBB0_521
	s_lshl_b32 s0, s16, 16
	s_add_u32 s4, s83, s0
	s_addc_u32 s5, s82, 0
	v_lshlrev_b32_e32 v34, 4, v163
	v_add_u32_e32 v35, 0x2000, v34
	v_add_u32_e32 v36, 0x4000, v34
	v_add_u32_e32 v37, 0x6000, v34
	v_add_u32_e32 v38, 0x8000, v34
	v_add_u32_e32 v39, 0xa000, v34
	v_add_u32_e32 v40, 0xc000, v34
	v_add_u32_e32 v41, 0xe000, v34
	global_load_dwordx4 v[2:5], v34, s[4:5]
	global_load_dwordx4 v[6:9], v35, s[4:5]
	global_load_dwordx4 v[10:13], v36, s[4:5]
	global_load_dwordx4 v[14:17], v37, s[4:5]
	global_load_dwordx4 v[18:21], v38, s[4:5]
	global_load_dwordx4 v[22:25], v39, s[4:5]
	global_load_dwordx4 v[26:29], v40, s[4:5]
	global_load_dwordx4 v[30:33], v41, s[4:5]
	v_lshrrev_b32_e32 v42, 5, v163
	v_and_b32_e32 v43, 31, v163
	v_mul_u32_u24_e32 v42, 0x210, v42
	v_lshl_add_u32 v42, v43, 4, v42
	s_waitcnt vmcnt(7)
	ds_write_b128 v42, v[2:5]
	s_waitcnt vmcnt(6)
	ds_write_b128 v42, v[6:9] offset:8448
	s_waitcnt vmcnt(5)
	ds_write_b128 v42, v[10:13] offset:16896
	s_waitcnt vmcnt(4)
	ds_write_b128 v42, v[14:17] offset:25344
	s_waitcnt vmcnt(3)
	ds_write_b128 v42, v[18:21] offset:33792
	s_waitcnt vmcnt(2)
	ds_write_b128 v42, v[22:25] offset:42240
	s_waitcnt vmcnt(1)
	ds_write_b128 v42, v[26:29] offset:50688
	s_waitcnt vmcnt(0)
	ds_write_b128 v42, v[30:33] offset:59136
